# NSA selected blocks: QK block without per-element limit compares when every lane's limit covers the whole tile (on top of window fast path)
# baseline (speedup 1.0000x reference)
; #define SB0 __builtin_amdgcn_sched_barrier(0)
; __device__ __forceinline__ void qk64_lim(const bf16x8 (&kq)[8], const bf16x8 (&qf)[2], float scale, int lim2,
;                                          f32x4 (&st)[4]) {
; #pragma unroll
;   for (int kt = 0; kt < 4; ++kt) {
;     f32x4 z = {0.f, 0.f, 0.f, 0.f};
;     z = mfma16(kq[2 * kt], qf[0], z);
;     z = mfma16(kq[2 * kt + 1], qf[1], z);
; #pragma unroll
;     for (int r = 0; r < 4; ++r) st[kt][r] = ((kt * 16 + r) <= lim2) ? z[r] * scale : -INFINITY;
;   }
; }
; __device__ __forceinline__ void phase_nsa_attn(const Params& p, char* smem, volatile LAS unsigned* vb_) {
;     ...
;       for (int i = 0; i < ntot; ++i) {
;         const int j = jn;
;         if (i + 1 < ntot) advance();
;         const bool mine = (((j < 64) ? (my0 >> j) : (my1 >> (j - 64))) & 1ull) != 0ull;
;         const int lim2 = (mine ? ((j == cur) ? (s - j * 64) : 63) : -1) - q * 4;
;         f32x4 st[4];
;         qk64_lim(kA, qf, scale, lim2, st);
;         SB0;
;         k_load64(kA, Ks + (size_t)jn * 4096, lane);
;         SB0;
;         softmax_update(st, m, lsum, o);
;         pv64(vA, st, o);
;         SB0;
;         v_load64(vA, Vs + (size_t)jn * 4096, lane);
;         SB0;
.LBB0_178:
	s_cmp_lt_i32 s36, 64
	s_waitcnt vmcnt(15)
	v_mfma_f32_16x16x32_bf16 v[88:91], v[88:91], v[4:7], 0
	s_cselect_b64 vcc, -1, 0
	s_sub_i32 s0, s36, 64
	v_lshrrev_b64 v[2:3], s36, v[92:93]
	v_lshrrev_b64 v[98:99], s0, v[94:95]
	s_cmp_eq_u32 s36, s60
	v_cndmask_b32_e32 v0, v98, v2, vcc
	s_cselect_b64 vcc, -1, 0
	s_lshl_b32 s0, s36, 6
	v_subrev_u32_e32 v2, s0, v155
	v_and_b32_e32 v0, 1, v0
	s_waitcnt vmcnt(14)
	v_mfma_f32_16x16x32_bf16 v[84:87], v[84:87], v[8:11], v[88:91]
	v_cndmask_b32_e32 v2, 63, v2, vcc
	v_cmp_eq_u32_e32 vcc, 1, v0
	s_waitcnt vmcnt(13)
	v_mfma_f32_16x16x32_bf16 v[80:83], v[80:83], v[4:7], 0
	v_cndmask_b32_e32 v0, -1, v2, vcc
	v_sub_u32_e32 v0, v0, v150
	v_cmp_lt_i32_e32 vcc, 50, v0
	s_cmp_eq_u64 vcc, exec
	s_cbranch_scc1 .Lsel_fast
	s_nop 1
	v_mul_f32_e32 v2, 0x3e38aa3b, v84
	v_cmp_lt_i32_e32 vcc, -1, v0
	s_waitcnt vmcnt(12)
	v_mfma_f32_16x16x32_bf16 v[76:79], v[76:79], v[8:11], v[80:83]
	v_cndmask_b32_e32 v101, v203, v2, vcc
	v_mul_f32_e32 v2, 0x3e38aa3b, v85
	s_waitcnt vmcnt(11)
	v_mfma_f32_16x16x32_bf16 v[60:63], v[60:63], v[4:7], 0
	v_cmp_lt_i32_e32 vcc, 0, v0
	s_nop 1
	v_cndmask_b32_e32 v99, v203, v2, vcc
	v_mul_f32_e32 v2, 0x3e38aa3b, v86
	v_cmp_lt_i32_e32 vcc, 1, v0
	s_waitcnt vmcnt(10)
	v_mfma_f32_16x16x32_bf16 v[52:55], v[52:55], v[8:11], v[60:63]
	v_cndmask_b32_e32 v98, v203, v2, vcc
	v_mul_f32_e32 v2, 0x3e38aa3b, v87
	v_cmp_lt_i32_e32 vcc, 2, v0
	s_waitcnt vmcnt(9)
	v_mfma_f32_16x16x32_bf16 v[44:47], v[44:47], v[4:7], 0
	v_cndmask_b32_e32 v3, v203, v2, vcc
	v_mul_f32_e32 v2, 0x3e38aa3b, v76
	v_cmp_lt_i32_e32 vcc, 15, v0
	s_waitcnt vmcnt(8)
	v_mfma_f32_16x16x32_bf16 v[28:31], v[28:31], v[8:11], v[44:47]
	v_cndmask_b32_e32 v105, v203, v2, vcc
	v_mul_f32_e32 v2, 0x3e38aa3b, v77
	v_cmp_lt_i32_e32 vcc, 16, v0
	s_nop 1
	v_cndmask_b32_e32 v103, v203, v2, vcc
	v_mul_f32_e32 v2, 0x3e38aa3b, v78
	v_cmp_lt_i32_e32 vcc, 17, v0
	s_nop 1
	v_cndmask_b32_e32 v102, v203, v2, vcc
	v_mul_f32_e32 v2, 0x3e38aa3b, v79
	v_cmp_lt_i32_e32 vcc, 18, v0
	s_nop 1
	v_cndmask_b32_e32 v100, v203, v2, vcc
	v_mul_f32_e32 v2, 0x3e38aa3b, v52
	v_cmp_lt_i32_e32 vcc, 31, v0
	s_nop 1
	v_cndmask_b32_e32 v108, v203, v2, vcc
	v_mul_f32_e32 v2, 0x3e38aa3b, v53
	v_cmp_lt_i32_e32 vcc, 32, v0
	s_nop 1
	v_cndmask_b32_e32 v107, v203, v2, vcc
	v_mul_f32_e32 v2, 0x3e38aa3b, v54
	v_cmp_lt_i32_e32 vcc, 33, v0
	s_nop 1
	v_cndmask_b32_e32 v106, v203, v2, vcc
	v_mul_f32_e32 v2, 0x3e38aa3b, v55
	v_cmp_lt_i32_e32 vcc, 34, v0
	s_nop 1
	v_cndmask_b32_e32 v104, v203, v2, vcc
	v_mul_f32_e32 v2, 0x3e38aa3b, v28
	v_cmp_lt_i32_e32 vcc, 47, v0
	s_nop 1
	v_cndmask_b32_e32 v109, v203, v2, vcc
	v_mul_f32_e32 v2, 0x3e38aa3b, v29
	v_cmp_lt_i32_e32 vcc, 48, v0
	s_nop 1
	v_cndmask_b32_e32 v110, v203, v2, vcc
	v_mul_f32_e32 v2, 0x3e38aa3b, v30
	v_cmp_lt_i32_e32 vcc, 49, v0
	s_nop 1
	v_cndmask_b32_e32 v111, v203, v2, vcc
	v_mul_f32_e32 v2, 0x3e38aa3b, v31
	v_cmp_lt_i32_e32 vcc, 50, v0
	s_nop 1
	v_cndmask_b32_e32 v112, v203, v2, vcc
	s_lshl_b64 s[0:1], s[58:59], 13
	v_lshl_add_u64 v[28:29], v[146:147], 0, s[0:1]
	global_load_dwordx4 v[88:91], v[28:29], off
	global_load_dwordx4 v[84:87], v[28:29], off offset:1024
	global_load_dwordx4 v[80:83], v[28:29], off offset:2048
	global_load_dwordx4 v[76:79], v[28:29], off offset:3072
	v_add_co_u32_e32 v28, vcc, s33, v28
	s_nop 1
	v_addc_co_u32_e32 v29, vcc, 0, v29, vcc
	global_load_dwordx4 v[60:63], v[28:29], off
	global_load_dwordx4 v[52:55], v[28:29], off offset:1024
	global_load_dwordx4 v[44:47], v[28:29], off offset:2048
	s_nop 0
	global_load_dwordx4 v[28:31], v[28:29], off offset:3072
	v_max3_f32 v0, v101, s3, v99
	v_max3_f32 v0, v0, v98, v3
	v_max3_f32 v0, v0, v105, v103
	v_max3_f32 v0, v0, v102, v100
	v_max3_f32 v0, v0, v108, v107
	v_max3_f32 v0, v0, v106, v104
	v_max3_f32 v0, v0, v109, v110
	v_max3_f32 v0, v0, v111, v112
	v_mov_b32_e32 v2, v0
	s_nop 1
	v_permlane16_swap_b32_e32 v2, v0
	v_max_f32_e32 v0, v0, v2
	v_mov_b32_e32 v2, v0
	s_nop 1
	v_permlane32_swap_b32_e32 v2, v0
	v_max3_f32 v2, v97, v0, v2
	v_sub_f32_e32 v0, v97, v2
	v_exp_f32_e32 v0, v0
	s_nop 0
	v_cmp_neq_f32_e32 vcc, 1.0, v0
	s_cbranch_vccz .LBB0_180
	v_pk_mul_f32 v[26:27], v[26:27], v[0:1] op_sel_hi:[1,0]
	v_pk_mul_f32 v[24:25], v[24:25], v[0:1] op_sel_hi:[1,0]
	v_pk_mul_f32 v[22:23], v[22:23], v[0:1] op_sel_hi:[1,0]
	v_pk_mul_f32 v[20:21], v[20:21], v[0:1] op_sel_hi:[1,0]
	v_pk_mul_f32 v[18:19], v[18:19], v[0:1] op_sel_hi:[1,0]
	v_pk_mul_f32 v[16:17], v[16:17], v[0:1] op_sel_hi:[1,0]
	v_pk_mul_f32 v[14:15], v[14:15], v[0:1] op_sel_hi:[1,0]
	v_pk_mul_f32 v[12:13], v[12:13], v[0:1] op_sel_hi:[1,0]

; #define EXP2F(x) __builtin_amdgcn_exp2f(x)
; #define SB0 __builtin_amdgcn_sched_barrier(0)
; __device__ __forceinline__ void softmax_update(f32x4 (&st)[4], float& m, float& lsum, f32x4 (&o)[4]) {
;   float mx = -1e30f;
; #pragma unroll
;   for (int kt = 0; kt < 4; ++kt)
; #pragma unroll
;     for (int r = 0; r < 4; ++r) mx = fmaxf(mx, st[kt][r]);
;   mx = fmaxf(mx, __shfl_xor(mx, 16));
;   mx = fmaxf(mx, __shfl_xor(mx, 32));
;   const float mnew = fmaxf(m, mx);
;   const float alpha = EXP2F(m - mnew);
;   float ps = 0.f;
; #pragma unroll
;   for (int kt = 0; kt < 4; ++kt)
; #pragma unroll
;     for (int r = 0; r < 4; ++r) {
;       const float pv = EXP2F(st[kt][r] - mnew);
;       st[kt][r] = pv;
;       ps += pv;
;     }
;   lsum = lsum * alpha + ps;
;   m = mnew;
;   if (__builtin_amdgcn_ballot_w64(alpha != 1.0f)) {
; #pragma unroll
;     for (int dt = 0; dt < 4; ++dt) o[dt] *= alpha;
;   }
; __device__ __forceinline__ void phase_nsa_attn(const Params& p, char* smem, volatile LAS unsigned* vb_) {
;     ...
;         qk64_lim(kA, qf, scale, lim2, st);
;         SB0;
;         k_load64(kA, Ks + (size_t)jn * 4096, lane);
;         SB0;
;         softmax_update(st, m, lsum, o);
;         pv64(vA, st, o);
;         SB0;
;         v_load64(vA, Vs + (size_t)jn * 4096, lane);
;         SB0;
.Lsel_fast:
	s_waitcnt vmcnt(12)
	v_mfma_f32_16x16x32_bf16 v[76:79], v[76:79], v[8:11], v[80:83]
	s_waitcnt vmcnt(11)
	v_mfma_f32_16x16x32_bf16 v[60:63], v[60:63], v[4:7], 0
	s_waitcnt vmcnt(10)
	v_mfma_f32_16x16x32_bf16 v[52:55], v[52:55], v[8:11], v[60:63]
	s_waitcnt vmcnt(9)
	v_mfma_f32_16x16x32_bf16 v[44:47], v[44:47], v[4:7], 0
	s_waitcnt vmcnt(8)
	v_mfma_f32_16x16x32_bf16 v[28:31], v[28:31], v[8:11], v[44:47]
	v_mul_f32_e32 v101, 0x3e38aa3b, v84
	v_mul_f32_e32 v99, 0x3e38aa3b, v85
	v_mul_f32_e32 v98, 0x3e38aa3b, v86
	v_mul_f32_e32 v3, 0x3e38aa3b, v87
	v_mul_f32_e32 v105, 0x3e38aa3b, v76
	v_mul_f32_e32 v103, 0x3e38aa3b, v77
	v_mul_f32_e32 v102, 0x3e38aa3b, v78
	v_mul_f32_e32 v100, 0x3e38aa3b, v79
	v_mul_f32_e32 v108, 0x3e38aa3b, v52
	v_mul_f32_e32 v107, 0x3e38aa3b, v53
	v_mul_f32_e32 v106, 0x3e38aa3b, v54
	v_mul_f32_e32 v104, 0x3e38aa3b, v55
	v_mul_f32_e32 v109, 0x3e38aa3b, v28
	v_mul_f32_e32 v110, 0x3e38aa3b, v29
	v_mul_f32_e32 v111, 0x3e38aa3b, v30
	v_mul_f32_e32 v112, 0x3e38aa3b, v31
	s_lshl_b64 s[0:1], s[58:59], 13
	v_lshl_add_u64 v[28:29], v[146:147], 0, s[0:1]
	global_load_dwordx4 v[88:91], v[28:29], off
	global_load_dwordx4 v[84:87], v[28:29], off offset:1024
	global_load_dwordx4 v[80:83], v[28:29], off offset:2048
	global_load_dwordx4 v[76:79], v[28:29], off offset:3072
	v_add_co_u32_e32 v28, vcc, s33, v28
	s_nop 1
	v_addc_co_u32_e32 v29, vcc, 0, v29, vcc
	global_load_dwordx4 v[60:63], v[28:29], off
	global_load_dwordx4 v[52:55], v[28:29], off offset:1024
	global_load_dwordx4 v[44:47], v[28:29], off offset:2048
	s_nop 0
	global_load_dwordx4 v[28:31], v[28:29], off offset:3072
	v_max3_f32 v0, v101, s3, v99
	v_max3_f32 v0, v0, v98, v3
	v_max3_f32 v0, v0, v105, v103
	v_max3_f32 v0, v0, v102, v100
	v_max3_f32 v0, v0, v108, v107
	v_max3_f32 v0, v0, v106, v104
	v_max3_f32 v0, v0, v109, v110
	v_max3_f32 v0, v0, v111, v112
	v_mov_b32_e32 v2, v0
	s_nop 1
	v_permlane16_swap_b32_e32 v2, v0
	v_max_f32_e32 v0, v0, v2
	v_mov_b32_e32 v2, v0
	s_nop 1
	v_permlane32_swap_b32_e32 v2, v0
	v_max3_f32 v2, v97, v0, v2
	v_sub_f32_e32 v0, v97, v2
	v_exp_f32_e32 v0, v0
	s_nop 0
	v_cmp_neq_f32_e32 vcc, 1.0, v0
	s_cbranch_vccz .LBB0_180
	v_pk_mul_f32 v[26:27], v[26:27], v[0:1] op_sel_hi:[1,0]
	v_pk_mul_f32 v[24:25], v[24:25], v[0:1] op_sel_hi:[1,0]
	v_pk_mul_f32 v[22:23], v[22:23], v[0:1] op_sel_hi:[1,0]
	v_pk_mul_f32 v[20:21], v[20:21], v[0:1] op_sel_hi:[1,0]
	v_pk_mul_f32 v[18:19], v[18:19], v[0:1] op_sel_hi:[1,0]
	v_pk_mul_f32 v[16:17], v[16:17], v[0:1] op_sel_hi:[1,0]
	v_pk_mul_f32 v[14:15], v[14:15], v[0:1] op_sel_hi:[1,0]
	v_pk_mul_f32 v[12:13], v[12:13], v[0:1] op_sel_hi:[1,0]
	s_branch .LBB0_180
